# GEMM unit prologues: accumulators cleared once with 64 v_mov_b64 instead of twice with 256 v_mov_b32
# speedup vs baseline: 1.0049x; 1.0049x over previous
; template <class Epi, class Sched, bool ALIGN_EPI = false, bool SP2 = false>
; __device__ __forceinline__ void gemm_phase(PG8_LAS unsigned char* lds, const Gemm g, const Sched& S, const Epi& E) {
;     ...
;     f32x4 acc[2][2][4][2];
; #pragma unroll
;     for (int a = 0; a < 2; ++a)
; #pragma unroll
;         for (int b = 0; b < 2; ++b)
; #pragma unroll
;             for (int m = 0; m < 4; ++m)
; #pragma unroll
;                 for (int n = 0; n < 2; ++n) acc[a][b][m][n] = (f32x4){0.f, 0.f, 0.f, 0.f};
;     bf16x8 At[4][2], B0[2][2], B1[2][2];
;     const char* cA = (const char*)g.A + (size_t)cur.pm * tstepA; const char* cB = (const char*)g.Bt + (size_t)cur.pn * tstep;
;     ...
;         for (int a = 0; a < 2; ++a)
; #pragma unroll
;             for (int b = 0; b < 2; ++b)
; #pragma unroll
;                 for (int m = 0; m < 4; ++m)
; #pragma unroll
;                     for (int n = 0; n < 2; ++n) acc[a][b][m][n] = (f32x4){0.f, 0.f, 0.f, 0.f};
;         cur = nxt; cA = nA; cB = nB; ++ui;
.LBB0_256:
	s_ashr_i32 s29, s28, 31
	s_lshl_b64 s[34:35], s[28:29], 19
	s_add_u32 s34, s44, s34
	v_mov_b64_e32 v[0:1], 0
	v_mov_b64_e32 v[2:3], 0
	v_mov_b64_e32 v[4:5], 0
	v_mov_b64_e32 v[6:7], 0
	v_mov_b64_e32 v[8:9], 0
	v_mov_b64_e32 v[10:11], 0
	v_mov_b64_e32 v[12:13], 0
	v_mov_b64_e32 v[14:15], 0
	v_mov_b64_e32 v[16:17], 0
	v_mov_b64_e32 v[18:19], 0
	v_mov_b64_e32 v[20:21], 0
	v_mov_b64_e32 v[22:23], 0
	v_mov_b64_e32 v[24:25], 0
	v_mov_b64_e32 v[26:27], 0
	v_mov_b64_e32 v[28:29], 0
	v_mov_b64_e32 v[30:31], 0
	v_mov_b64_e32 v[32:33], 0
	v_mov_b64_e32 v[34:35], 0
	v_mov_b64_e32 v[36:37], 0
	v_mov_b64_e32 v[38:39], 0
	v_mov_b64_e32 v[40:41], 0
	v_mov_b64_e32 v[42:43], 0
	v_mov_b64_e32 v[44:45], 0
	v_mov_b64_e32 v[46:47], 0
	v_mov_b64_e32 v[48:49], 0
	v_mov_b64_e32 v[50:51], 0
	v_mov_b64_e32 v[52:53], 0
	v_mov_b64_e32 v[54:55], 0
	v_mov_b64_e32 v[56:57], 0
	v_mov_b64_e32 v[58:59], 0
	v_mov_b64_e32 v[60:61], 0
	v_mov_b64_e32 v[62:63], 0
	v_mov_b64_e32 v[64:65], 0
	v_mov_b64_e32 v[66:67], 0
	v_mov_b64_e32 v[68:69], 0
	v_mov_b64_e32 v[70:71], 0
	v_mov_b64_e32 v[72:73], 0
	v_mov_b64_e32 v[74:75], 0
	v_mov_b64_e32 v[76:77], 0
	v_mov_b64_e32 v[78:79], 0
	v_mov_b64_e32 v[80:81], 0
	v_mov_b64_e32 v[82:83], 0
	v_mov_b64_e32 v[84:85], 0
	v_mov_b64_e32 v[86:87], 0
	v_mov_b64_e32 v[88:89], 0
	v_mov_b64_e32 v[90:91], 0
	v_mov_b64_e32 v[92:93], 0
	v_mov_b64_e32 v[94:95], 0
	v_mov_b64_e32 v[96:97], 0
	v_mov_b64_e32 v[98:99], 0
	v_mov_b64_e32 v[100:101], 0
	v_mov_b64_e32 v[102:103], 0
	v_mov_b64_e32 v[104:105], 0
	v_mov_b64_e32 v[106:107], 0
	v_mov_b64_e32 v[108:109], 0
	v_mov_b64_e32 v[110:111], 0
	v_mov_b64_e32 v[112:113], 0
	v_mov_b64_e32 v[114:115], 0
	v_mov_b64_e32 v[116:117], 0
	v_mov_b64_e32 v[118:119], 0
	v_mov_b64_e32 v[120:121], 0
	v_mov_b64_e32 v[122:123], 0
	v_mov_b64_e32 v[124:125], 0
	v_mov_b64_e32 v[126:127], 0
	s_addc_u32 s35, s45, s35
	s_and_b64 vcc, exec, s[6:7]
	s_cbranch_vccnz .LBB0_259
	s_and_b64 s[10:11], s[10:11], exec
	s_cselect_b32 s29, s35, s39
	s_cselect_b32 s64, s34, s38
	s_add_u32 s10, s38, 0x40080
	s_addc_u32 s11, s39, 0
	s_add_u32 s38, s36, 0x100
	s_addc_u32 s39, s37, 0
	s_mov_b32 s36, 0

; template <class Epi, class Sched, bool ALIGN_EPI = false, bool SP2 = false>
; __device__ __forceinline__ void gemm_phase(PG8_LAS unsigned char* lds, const Gemm g, const Sched& S, const Epi& E) {
;     ...
;     f32x4 acc[2][2][4][2];
; #pragma unroll
;     for (int a = 0; a < 2; ++a)
; #pragma unroll
;         for (int b = 0; b < 2; ++b)
; #pragma unroll
;             for (int m = 0; m < 4; ++m)
; #pragma unroll
;                 for (int n = 0; n < 2; ++n) acc[a][b][m][n] = (f32x4){0.f, 0.f, 0.f, 0.f};
;     bf16x8 At[4][2], B0[2][2], B1[2][2];
;     const char* cA = (const char*)g.A + (size_t)cur.pm * tstepA; const char* cB = (const char*)g.Bt + (size_t)cur.pn * tstep;
;     ...
;         for (int a = 0; a < 2; ++a)
; #pragma unroll
;             for (int b = 0; b < 2; ++b)
; #pragma unroll
;                 for (int m = 0; m < 4; ++m)
; #pragma unroll
;                     for (int n = 0; n < 2; ++n) acc[a][b][m][n] = (f32x4){0.f, 0.f, 0.f, 0.f};
;         cur = nxt; cA = nA; cB = nB; ++ui;
.LBB0_280:
	s_ashr_i32 s5, s4, 31
	s_lshl_b64 s[28:29], s[4:5], 19
	s_add_u32 s28, s38, s28
	v_mov_b64_e32 v[0:1], 0
	v_mov_b64_e32 v[2:3], 0
	v_mov_b64_e32 v[4:5], 0
	v_mov_b64_e32 v[6:7], 0
	v_mov_b64_e32 v[8:9], 0
	v_mov_b64_e32 v[10:11], 0
	v_mov_b64_e32 v[12:13], 0
	v_mov_b64_e32 v[14:15], 0
	v_mov_b64_e32 v[16:17], 0
	v_mov_b64_e32 v[18:19], 0
	v_mov_b64_e32 v[20:21], 0
	v_mov_b64_e32 v[22:23], 0
	v_mov_b64_e32 v[24:25], 0
	v_mov_b64_e32 v[26:27], 0
	v_mov_b64_e32 v[28:29], 0
	v_mov_b64_e32 v[30:31], 0
	v_mov_b64_e32 v[32:33], 0
	v_mov_b64_e32 v[34:35], 0
	v_mov_b64_e32 v[36:37], 0
	v_mov_b64_e32 v[38:39], 0
	v_mov_b64_e32 v[40:41], 0
	v_mov_b64_e32 v[42:43], 0
	v_mov_b64_e32 v[44:45], 0
	v_mov_b64_e32 v[46:47], 0
	v_mov_b64_e32 v[48:49], 0
	v_mov_b64_e32 v[50:51], 0
	v_mov_b64_e32 v[52:53], 0
	v_mov_b64_e32 v[54:55], 0
	v_mov_b64_e32 v[56:57], 0
	v_mov_b64_e32 v[58:59], 0
	v_mov_b64_e32 v[60:61], 0
	v_mov_b64_e32 v[62:63], 0
	v_mov_b64_e32 v[64:65], 0
	v_mov_b64_e32 v[66:67], 0
	v_mov_b64_e32 v[68:69], 0
	v_mov_b64_e32 v[70:71], 0
	v_mov_b64_e32 v[72:73], 0
	v_mov_b64_e32 v[74:75], 0
	v_mov_b64_e32 v[76:77], 0
	v_mov_b64_e32 v[78:79], 0
	v_mov_b64_e32 v[80:81], 0
	v_mov_b64_e32 v[82:83], 0
	v_mov_b64_e32 v[84:85], 0
	v_mov_b64_e32 v[86:87], 0
	v_mov_b64_e32 v[88:89], 0
	v_mov_b64_e32 v[90:91], 0
	v_mov_b64_e32 v[92:93], 0
	v_mov_b64_e32 v[94:95], 0
	v_mov_b64_e32 v[96:97], 0
	v_mov_b64_e32 v[98:99], 0
	v_mov_b64_e32 v[100:101], 0
	v_mov_b64_e32 v[102:103], 0
	v_mov_b64_e32 v[104:105], 0
	v_mov_b64_e32 v[106:107], 0
	v_mov_b64_e32 v[108:109], 0
	v_mov_b64_e32 v[110:111], 0
	v_mov_b64_e32 v[112:113], 0
	v_mov_b64_e32 v[114:115], 0
	v_mov_b64_e32 v[116:117], 0
	v_mov_b64_e32 v[118:119], 0
	v_mov_b64_e32 v[120:121], 0
	v_mov_b64_e32 v[122:123], 0
	v_mov_b64_e32 v[124:125], 0
	v_mov_b64_e32 v[126:127], 0
	s_addc_u32 s29, s39, s29
	s_and_b64 vcc, exec, s[6:7]
	s_cbranch_vccnz .LBB0_283
	s_and_b64 s[36:37], s[36:37], exec
	s_cselect_b32 s5, s29, s31
	s_cselect_b32 s36, s28, s30
	s_add_u32 s30, s30, 0x40080
	s_addc_u32 s31, s31, 0
	s_add_u32 s37, s34, 0x100
	s_addc_u32 s60, s35, 0
	s_mov_b32 s34, 0

; template <class Epi, class Sched, bool ALIGN_EPI = false, bool SP2 = false>
; __device__ __forceinline__ void gemm_phase(PG8_LAS unsigned char* lds, const Gemm g, const Sched& S, const Epi& E) {
;     ...
;     f32x4 acc[2][2][4][2];
; #pragma unroll
;     for (int a = 0; a < 2; ++a)
; #pragma unroll
;         for (int b = 0; b < 2; ++b)
; #pragma unroll
;             for (int m = 0; m < 4; ++m)
; #pragma unroll
;                 for (int n = 0; n < 2; ++n) acc[a][b][m][n] = (f32x4){0.f, 0.f, 0.f, 0.f};
;     bf16x8 At[4][2], B0[2][2], B1[2][2];
;     const char* cA = (const char*)g.A + (size_t)cur.pm * tstepA; const char* cB = (const char*)g.Bt + (size_t)cur.pn * tstep;
;     ...
;         for (int a = 0; a < 2; ++a)
; #pragma unroll
;             for (int b = 0; b < 2; ++b)
; #pragma unroll
;                 for (int m = 0; m < 4; ++m)
; #pragma unroll
;                     for (int n = 0; n < 2; ++n) acc[a][b][m][n] = (f32x4){0.f, 0.f, 0.f, 0.f};
;         cur = nxt; cA = nA; cB = nB; ++ui;
.LBB0_366:
	s_and_b64 s[24:25], s[8:9], exec
	s_cselect_b32 s13, s22, s30
	s_ashr_i64 s[24:25], s[12:13], 14
	s_add_u32 s24, s33, s24
	v_mov_b64_e32 v[0:1], 0
	v_mov_b64_e32 v[2:3], 0
	v_mov_b64_e32 v[4:5], 0
	v_mov_b64_e32 v[6:7], 0
	v_mov_b64_e32 v[8:9], 0
	v_mov_b64_e32 v[10:11], 0
	v_mov_b64_e32 v[12:13], 0
	v_mov_b64_e32 v[14:15], 0
	v_mov_b64_e32 v[16:17], 0
	v_mov_b64_e32 v[18:19], 0
	v_mov_b64_e32 v[20:21], 0
	v_mov_b64_e32 v[22:23], 0
	v_mov_b64_e32 v[24:25], 0
	v_mov_b64_e32 v[26:27], 0
	v_mov_b64_e32 v[28:29], 0
	v_mov_b64_e32 v[30:31], 0
	v_mov_b64_e32 v[32:33], 0
	v_mov_b64_e32 v[34:35], 0
	v_mov_b64_e32 v[36:37], 0
	v_mov_b64_e32 v[38:39], 0
	v_mov_b64_e32 v[40:41], 0
	v_mov_b64_e32 v[42:43], 0
	v_mov_b64_e32 v[44:45], 0
	v_mov_b64_e32 v[46:47], 0
	v_mov_b64_e32 v[48:49], 0
	v_mov_b64_e32 v[50:51], 0
	v_mov_b64_e32 v[52:53], 0
	v_mov_b64_e32 v[54:55], 0
	v_mov_b64_e32 v[56:57], 0
	v_mov_b64_e32 v[58:59], 0
	v_mov_b64_e32 v[60:61], 0
	v_mov_b64_e32 v[62:63], 0
	v_mov_b64_e32 v[64:65], 0
	v_mov_b64_e32 v[66:67], 0
	v_mov_b64_e32 v[68:69], 0
	v_mov_b64_e32 v[70:71], 0
	v_mov_b64_e32 v[72:73], 0
	v_mov_b64_e32 v[74:75], 0
	v_mov_b64_e32 v[76:77], 0
	v_mov_b64_e32 v[78:79], 0
	v_mov_b64_e32 v[80:81], 0
	v_mov_b64_e32 v[82:83], 0
	v_mov_b64_e32 v[84:85], 0
	v_mov_b64_e32 v[86:87], 0
	v_mov_b64_e32 v[88:89], 0
	v_mov_b64_e32 v[90:91], 0
	v_mov_b64_e32 v[92:93], 0
	v_mov_b64_e32 v[94:95], 0
	v_mov_b64_e32 v[96:97], 0
	v_mov_b64_e32 v[98:99], 0
	v_mov_b64_e32 v[100:101], 0
	v_mov_b64_e32 v[102:103], 0
	v_mov_b64_e32 v[104:105], 0
	v_mov_b64_e32 v[106:107], 0
	v_mov_b64_e32 v[108:109], 0
	v_mov_b64_e32 v[110:111], 0
	v_mov_b64_e32 v[112:113], 0
	v_mov_b64_e32 v[114:115], 0
	v_mov_b64_e32 v[116:117], 0
	v_mov_b64_e32 v[118:119], 0
	v_mov_b64_e32 v[120:121], 0
	v_mov_b64_e32 v[122:123], 0
	v_mov_b64_e32 v[124:125], 0
	v_mov_b64_e32 v[126:127], 0
	s_addc_u32 s25, s34, s25
	s_and_b64 vcc, exec, s[6:7]
	s_cbranch_vccnz .LBB0_369
	s_and_b64 s[62:63], s[8:9], exec
	s_cselect_b32 s13, s25, s27
	s_cselect_b32 s30, s24, s26
	s_add_u32 s26, s26, 0x20080
	s_addc_u32 s27, s27, 0
	s_add_u32 s62, s28, 0x100
	s_addc_u32 s63, s29, 0
	s_mov_b32 s28, 0

; template <class Epi, class Sched, bool ALIGN_EPI = false, bool SP2 = false>
; __device__ __forceinline__ void gemm_phase(PG8_LAS unsigned char* lds, const Gemm g, const Sched& S, const Epi& E) {
;     ...
;     f32x4 acc[2][2][4][2];
; #pragma unroll
;     for (int a = 0; a < 2; ++a)
; #pragma unroll
;         for (int b = 0; b < 2; ++b)
; #pragma unroll
;             for (int m = 0; m < 4; ++m)
; #pragma unroll
;                 for (int n = 0; n < 2; ++n) acc[a][b][m][n] = (f32x4){0.f, 0.f, 0.f, 0.f};
;     bf16x8 At[4][2], B0[2][2], B1[2][2];
;     const char* cA = (const char*)g.A + (size_t)cur.pm * tstepA; const char* cB = (const char*)g.Bt + (size_t)cur.pn * tstep;
;     ...
;         for (int a = 0; a < 2; ++a)
; #pragma unroll
;             for (int b = 0; b < 2; ++b)
; #pragma unroll
;                 for (int m = 0; m < 4; ++m)
; #pragma unroll
;                     for (int n = 0; n < 2; ++n) acc[a][b][m][n] = (f32x4){0.f, 0.f, 0.f, 0.f};
;         cur = nxt; cA = nA; cB = nB; ++ui;
.LBB0_521:
	s_and_b64 s[28:29], s[8:9], exec
	s_cselect_b32 s15, s26, s34
	s_ashr_i64 s[28:29], s[14:15], 14
	s_add_u32 s28, s36, s28
	v_mov_b64_e32 v[0:1], 0
	v_mov_b64_e32 v[2:3], 0
	v_mov_b64_e32 v[4:5], 0
	v_mov_b64_e32 v[6:7], 0
	v_mov_b64_e32 v[8:9], 0
	v_mov_b64_e32 v[10:11], 0
	v_mov_b64_e32 v[12:13], 0
	v_mov_b64_e32 v[14:15], 0
	v_mov_b64_e32 v[16:17], 0
	v_mov_b64_e32 v[18:19], 0
	v_mov_b64_e32 v[20:21], 0
	v_mov_b64_e32 v[22:23], 0
	v_mov_b64_e32 v[24:25], 0
	v_mov_b64_e32 v[26:27], 0
	v_mov_b64_e32 v[28:29], 0
	v_mov_b64_e32 v[30:31], 0
	v_mov_b64_e32 v[32:33], 0
	v_mov_b64_e32 v[34:35], 0
	v_mov_b64_e32 v[36:37], 0
	v_mov_b64_e32 v[38:39], 0
	v_mov_b64_e32 v[40:41], 0
	v_mov_b64_e32 v[42:43], 0
	v_mov_b64_e32 v[44:45], 0
	v_mov_b64_e32 v[46:47], 0
	v_mov_b64_e32 v[48:49], 0
	v_mov_b64_e32 v[50:51], 0
	v_mov_b64_e32 v[52:53], 0
	v_mov_b64_e32 v[54:55], 0
	v_mov_b64_e32 v[56:57], 0
	v_mov_b64_e32 v[58:59], 0
	v_mov_b64_e32 v[60:61], 0
	v_mov_b64_e32 v[62:63], 0
	v_mov_b64_e32 v[64:65], 0
	v_mov_b64_e32 v[66:67], 0
	v_mov_b64_e32 v[68:69], 0
	v_mov_b64_e32 v[70:71], 0
	v_mov_b64_e32 v[72:73], 0
	v_mov_b64_e32 v[74:75], 0
	v_mov_b64_e32 v[76:77], 0
	v_mov_b64_e32 v[78:79], 0
	v_mov_b64_e32 v[80:81], 0
	v_mov_b64_e32 v[82:83], 0
	v_mov_b64_e32 v[84:85], 0
	v_mov_b64_e32 v[86:87], 0
	v_mov_b64_e32 v[88:89], 0
	v_mov_b64_e32 v[90:91], 0
	v_mov_b64_e32 v[92:93], 0
	v_mov_b64_e32 v[94:95], 0
	v_mov_b64_e32 v[96:97], 0
	v_mov_b64_e32 v[98:99], 0
	v_mov_b64_e32 v[100:101], 0
	v_mov_b64_e32 v[102:103], 0
	v_mov_b64_e32 v[104:105], 0
	v_mov_b64_e32 v[106:107], 0
	v_mov_b64_e32 v[108:109], 0
	v_mov_b64_e32 v[110:111], 0
	v_mov_b64_e32 v[112:113], 0
	v_mov_b64_e32 v[114:115], 0
	v_mov_b64_e32 v[116:117], 0
	v_mov_b64_e32 v[118:119], 0
	v_mov_b64_e32 v[120:121], 0
	v_mov_b64_e32 v[122:123], 0
	v_mov_b64_e32 v[124:125], 0
	v_mov_b64_e32 v[126:127], 0
	s_addc_u32 s29, s37, s29
	s_and_b64 vcc, exec, s[6:7]
	s_cbranch_vccnz .LBB0_524
	s_and_b64 s[60:61], s[8:9], exec
	s_cselect_b32 s15, s29, s5
	s_cselect_b32 s34, s28, s4
	s_add_u32 s4, s4, 0x20080
	s_addc_u32 s5, s5, 0
	s_add_u32 s59, s30, 0x100
	s_addc_u32 s60, s31, 0
	s_mov_b32 s30, 0

; template <class Epi, class Sched, bool ALIGN_EPI = false, bool SP2 = false>
; __device__ __forceinline__ void gemm_phase(PG8_LAS unsigned char* lds, const Gemm g, const Sched& S, const Epi& E) {
;     ...
;     f32x4 acc[2][2][4][2];
; #pragma unroll
;     for (int a = 0; a < 2; ++a)
; #pragma unroll
;         for (int b = 0; b < 2; ++b)
; #pragma unroll
;             for (int m = 0; m < 4; ++m)
; #pragma unroll
;                 for (int n = 0; n < 2; ++n) acc[a][b][m][n] = (f32x4){0.f, 0.f, 0.f, 0.f};
;     bf16x8 At[4][2], B0[2][2], B1[2][2];
;     const char* cA = (const char*)g.A + (size_t)cur.pm * tstepA; const char* cB = (const char*)g.Bt + (size_t)cur.pn * tstep;
;     ...
;         for (int a = 0; a < 2; ++a)
; #pragma unroll
;             for (int b = 0; b < 2; ++b)
; #pragma unroll
;                 for (int m = 0; m < 4; ++m)
; #pragma unroll
;                     for (int n = 0; n < 2; ++n) acc[a][b][m][n] = (f32x4){0.f, 0.f, 0.f, 0.f};
;         cur = nxt; cA = nA; cB = nB; ++ui;
.LBB0_599:
	s_ashr_i32 s23, s22, 31
	s_lshl_b64 s[26:27], s[22:23], 19
	s_add_u32 s26, s3, s26
	v_mov_b64_e32 v[0:1], 0
	v_mov_b64_e32 v[2:3], 0
	v_mov_b64_e32 v[4:5], 0
	v_mov_b64_e32 v[6:7], 0
	v_mov_b64_e32 v[8:9], 0
	v_mov_b64_e32 v[10:11], 0
	v_mov_b64_e32 v[12:13], 0
	v_mov_b64_e32 v[14:15], 0
	v_mov_b64_e32 v[16:17], 0
	v_mov_b64_e32 v[18:19], 0
	v_mov_b64_e32 v[20:21], 0
	v_mov_b64_e32 v[22:23], 0
	v_mov_b64_e32 v[24:25], 0
	v_mov_b64_e32 v[26:27], 0
	v_mov_b64_e32 v[28:29], 0
	v_mov_b64_e32 v[30:31], 0
	v_mov_b64_e32 v[32:33], 0
	v_mov_b64_e32 v[34:35], 0
	v_mov_b64_e32 v[36:37], 0
	v_mov_b64_e32 v[38:39], 0
	v_mov_b64_e32 v[40:41], 0
	v_mov_b64_e32 v[42:43], 0
	v_mov_b64_e32 v[44:45], 0
	v_mov_b64_e32 v[46:47], 0
	v_mov_b64_e32 v[48:49], 0
	v_mov_b64_e32 v[50:51], 0
	v_mov_b64_e32 v[52:53], 0
	v_mov_b64_e32 v[54:55], 0
	v_mov_b64_e32 v[56:57], 0
	v_mov_b64_e32 v[58:59], 0
	v_mov_b64_e32 v[60:61], 0
	v_mov_b64_e32 v[62:63], 0
	v_mov_b64_e32 v[64:65], 0
	v_mov_b64_e32 v[66:67], 0
	v_mov_b64_e32 v[68:69], 0
	v_mov_b64_e32 v[70:71], 0
	v_mov_b64_e32 v[72:73], 0
	v_mov_b64_e32 v[74:75], 0
	v_mov_b64_e32 v[76:77], 0
	v_mov_b64_e32 v[78:79], 0
	v_mov_b64_e32 v[80:81], 0
	v_mov_b64_e32 v[82:83], 0
	v_mov_b64_e32 v[84:85], 0
	v_mov_b64_e32 v[86:87], 0
	v_mov_b64_e32 v[88:89], 0
	v_mov_b64_e32 v[90:91], 0
	v_mov_b64_e32 v[92:93], 0
	v_mov_b64_e32 v[94:95], 0
	v_mov_b64_e32 v[96:97], 0
	v_mov_b64_e32 v[98:99], 0
	v_mov_b64_e32 v[100:101], 0
	v_mov_b64_e32 v[102:103], 0
	v_mov_b64_e32 v[104:105], 0
	v_mov_b64_e32 v[106:107], 0
	v_mov_b64_e32 v[108:109], 0
	v_mov_b64_e32 v[110:111], 0
	v_mov_b64_e32 v[112:113], 0
	v_mov_b64_e32 v[114:115], 0
	v_mov_b64_e32 v[116:117], 0
	v_mov_b64_e32 v[118:119], 0
	v_mov_b64_e32 v[120:121], 0
	v_mov_b64_e32 v[122:123], 0
	v_mov_b64_e32 v[124:125], 0
	v_mov_b64_e32 v[126:127], 0
	s_addc_u32 s27, s33, s27
	s_and_b64 vcc, exec, s[6:7]
	s_cbranch_vccnz .LBB0_602
	s_and_b64 s[10:11], s[10:11], exec
	s_cselect_b32 s23, s27, s35
	s_cselect_b32 s59, s26, s34
	s_add_u32 s10, s34, 0x40080
	s_addc_u32 s11, s35, 0
	s_add_u32 s34, s30, 0x100
	s_addc_u32 s35, s31, 0
	s_mov_b32 s30, 0

; template <class Epi, class Sched, bool ALIGN_EPI = false, bool SP2 = false>
; __device__ __forceinline__ void gemm_phase(PG8_LAS unsigned char* lds, const Gemm g, const Sched& S, const Epi& E) {
;     ...
;     f32x4 acc[2][2][4][2];
; #pragma unroll
;     for (int a = 0; a < 2; ++a)
; #pragma unroll
;         for (int b = 0; b < 2; ++b)
; #pragma unroll
;             for (int m = 0; m < 4; ++m)
; #pragma unroll
;                 for (int n = 0; n < 2; ++n) acc[a][b][m][n] = (f32x4){0.f, 0.f, 0.f, 0.f};
;     bf16x8 At[4][2], B0[2][2], B1[2][2];
;     const char* cA = (const char*)g.A + (size_t)cur.pm * tstepA; const char* cB = (const char*)g.Bt + (size_t)cur.pn * tstep;
;     ...
;         for (int a = 0; a < 2; ++a)
; #pragma unroll
;             for (int b = 0; b < 2; ++b)
; #pragma unroll
;                 for (int m = 0; m < 4; ++m)
; #pragma unroll
;                     for (int n = 0; n < 2; ++n) acc[a][b][m][n] = (f32x4){0.f, 0.f, 0.f, 0.f};
;         cur = nxt; cA = nA; cB = nB; ++ui;
.LBB0_679:
	s_ashr_i32 s39, s38, 31
	s_lshl_b64 s[42:43], s[38:39], 19
	s_add_u32 s42, s3, s42
	v_mov_b64_e32 v[0:1], 0
	v_mov_b64_e32 v[2:3], 0
	v_mov_b64_e32 v[4:5], 0
	v_mov_b64_e32 v[6:7], 0
	v_mov_b64_e32 v[8:9], 0
	v_mov_b64_e32 v[10:11], 0
	v_mov_b64_e32 v[12:13], 0
	v_mov_b64_e32 v[14:15], 0
	v_mov_b64_e32 v[16:17], 0
	v_mov_b64_e32 v[18:19], 0
	v_mov_b64_e32 v[20:21], 0
	v_mov_b64_e32 v[22:23], 0
	v_mov_b64_e32 v[24:25], 0
	v_mov_b64_e32 v[26:27], 0
	v_mov_b64_e32 v[28:29], 0
	v_mov_b64_e32 v[30:31], 0
	v_mov_b64_e32 v[32:33], 0
	v_mov_b64_e32 v[34:35], 0
	v_mov_b64_e32 v[36:37], 0
	v_mov_b64_e32 v[38:39], 0
	v_mov_b64_e32 v[40:41], 0
	v_mov_b64_e32 v[42:43], 0
	v_mov_b64_e32 v[44:45], 0
	v_mov_b64_e32 v[46:47], 0
	v_mov_b64_e32 v[48:49], 0
	v_mov_b64_e32 v[50:51], 0
	v_mov_b64_e32 v[52:53], 0
	v_mov_b64_e32 v[54:55], 0
	v_mov_b64_e32 v[56:57], 0
	v_mov_b64_e32 v[58:59], 0
	v_mov_b64_e32 v[60:61], 0
	v_mov_b64_e32 v[62:63], 0
	v_mov_b64_e32 v[64:65], 0
	v_mov_b64_e32 v[66:67], 0
	v_mov_b64_e32 v[68:69], 0
	v_mov_b64_e32 v[70:71], 0
	v_mov_b64_e32 v[72:73], 0
	v_mov_b64_e32 v[74:75], 0
	v_mov_b64_e32 v[76:77], 0
	v_mov_b64_e32 v[78:79], 0
	v_mov_b64_e32 v[80:81], 0
	v_mov_b64_e32 v[82:83], 0
	v_mov_b64_e32 v[84:85], 0
	v_mov_b64_e32 v[86:87], 0
	v_mov_b64_e32 v[88:89], 0
	v_mov_b64_e32 v[90:91], 0
	v_mov_b64_e32 v[92:93], 0
	v_mov_b64_e32 v[94:95], 0
	v_mov_b64_e32 v[96:97], 0
	v_mov_b64_e32 v[98:99], 0
	v_mov_b64_e32 v[100:101], 0
	v_mov_b64_e32 v[102:103], 0
	v_mov_b64_e32 v[104:105], 0
	v_mov_b64_e32 v[106:107], 0
	v_mov_b64_e32 v[108:109], 0
	v_mov_b64_e32 v[110:111], 0
	v_mov_b64_e32 v[112:113], 0
	v_mov_b64_e32 v[114:115], 0
	v_mov_b64_e32 v[116:117], 0
	v_mov_b64_e32 v[118:119], 0
	v_mov_b64_e32 v[120:121], 0
	v_mov_b64_e32 v[122:123], 0
	v_mov_b64_e32 v[124:125], 0
	v_mov_b64_e32 v[126:127], 0
	s_addc_u32 s43, s33, s43
	s_andn2_b64 vcc, exec, s[24:25]
	s_cbranch_vccnz .LBB0_682
	s_and_b64 s[8:9], s[8:9], exec
	s_cselect_b32 s39, s43, s51
	s_cselect_b32 s70, s42, s50
	s_add_u32 s8, s50, 0x40080
	s_addc_u32 s9, s51, 0
	s_add_u32 s50, s48, 0x100
	s_addc_u32 s51, s49, 0
	s_mov_b32 s48, 0

; template <class Epi, class Sched, bool ALIGN_EPI = false, bool SP2 = false>
; __device__ __forceinline__ void gemm_phase(PG8_LAS unsigned char* lds, const Gemm g, const Sched& S, const Epi& E) {
;     ...
;     f32x4 acc[2][2][4][2];
; #pragma unroll
;     for (int a = 0; a < 2; ++a)
; #pragma unroll
;         for (int b = 0; b < 2; ++b)
; #pragma unroll
;             for (int m = 0; m < 4; ++m)
; #pragma unroll
;                 for (int n = 0; n < 2; ++n) acc[a][b][m][n] = (f32x4){0.f, 0.f, 0.f, 0.f};
;     bf16x8 At[4][2], B0[2][2], B1[2][2];
;     const char* cA = (const char*)g.A + (size_t)cur.pm * tstepA; const char* cB = (const char*)g.Bt + (size_t)cur.pn * tstep;
;     ...
;         for (int a = 0; a < 2; ++a)
; #pragma unroll
;             for (int b = 0; b < 2; ++b)
; #pragma unroll
;                 for (int m = 0; m < 4; ++m)
; #pragma unroll
;                     for (int n = 0; n < 2; ++n) acc[a][b][m][n] = (f32x4){0.f, 0.f, 0.f, 0.f};
;         cur = nxt; cA = nA; cB = nB; ++ui;
.LBB0_760:
	s_ashr_i32 s37, s36, 31
	s_lshl_b64 s[40:41], s[36:37], 19
	s_add_u32 s40, s3, s40
	v_mov_b64_e32 v[0:1], 0
	v_mov_b64_e32 v[2:3], 0
	v_mov_b64_e32 v[4:5], 0
	v_mov_b64_e32 v[6:7], 0
	v_mov_b64_e32 v[8:9], 0
	v_mov_b64_e32 v[10:11], 0
	v_mov_b64_e32 v[12:13], 0
	v_mov_b64_e32 v[14:15], 0
	v_mov_b64_e32 v[16:17], 0
	v_mov_b64_e32 v[18:19], 0
	v_mov_b64_e32 v[20:21], 0
	v_mov_b64_e32 v[22:23], 0
	v_mov_b64_e32 v[24:25], 0
	v_mov_b64_e32 v[26:27], 0
	v_mov_b64_e32 v[28:29], 0
	v_mov_b64_e32 v[30:31], 0
	v_mov_b64_e32 v[32:33], 0
	v_mov_b64_e32 v[34:35], 0
	v_mov_b64_e32 v[36:37], 0
	v_mov_b64_e32 v[38:39], 0
	v_mov_b64_e32 v[40:41], 0
	v_mov_b64_e32 v[42:43], 0
	v_mov_b64_e32 v[44:45], 0
	v_mov_b64_e32 v[46:47], 0
	v_mov_b64_e32 v[48:49], 0
	v_mov_b64_e32 v[50:51], 0
	v_mov_b64_e32 v[52:53], 0
	v_mov_b64_e32 v[54:55], 0
	v_mov_b64_e32 v[56:57], 0
	v_mov_b64_e32 v[58:59], 0
	v_mov_b64_e32 v[60:61], 0
	v_mov_b64_e32 v[62:63], 0
	v_mov_b64_e32 v[64:65], 0
	v_mov_b64_e32 v[66:67], 0
	v_mov_b64_e32 v[68:69], 0
	v_mov_b64_e32 v[70:71], 0
	v_mov_b64_e32 v[72:73], 0
	v_mov_b64_e32 v[74:75], 0
	v_mov_b64_e32 v[76:77], 0
	v_mov_b64_e32 v[78:79], 0
	v_mov_b64_e32 v[80:81], 0
	v_mov_b64_e32 v[82:83], 0
	v_mov_b64_e32 v[84:85], 0
	v_mov_b64_e32 v[86:87], 0
	v_mov_b64_e32 v[88:89], 0
	v_mov_b64_e32 v[90:91], 0
	v_mov_b64_e32 v[92:93], 0
	v_mov_b64_e32 v[94:95], 0
	v_mov_b64_e32 v[96:97], 0
	v_mov_b64_e32 v[98:99], 0
	v_mov_b64_e32 v[100:101], 0
	v_mov_b64_e32 v[102:103], 0
	v_mov_b64_e32 v[104:105], 0
	v_mov_b64_e32 v[106:107], 0
	v_mov_b64_e32 v[108:109], 0
	v_mov_b64_e32 v[110:111], 0
	v_mov_b64_e32 v[112:113], 0
	v_mov_b64_e32 v[114:115], 0
	v_mov_b64_e32 v[116:117], 0
	v_mov_b64_e32 v[118:119], 0
	v_mov_b64_e32 v[120:121], 0
	v_mov_b64_e32 v[122:123], 0
	v_mov_b64_e32 v[124:125], 0
	v_mov_b64_e32 v[126:127], 0
	s_addc_u32 s41, s33, s41
	s_andn2_b64 vcc, exec, s[22:23]
	s_cbranch_vccnz .LBB0_763
	s_and_b64 s[50:51], s[50:51], exec
	s_cselect_b32 s37, s41, s45
	s_cselect_b32 s50, s40, s44
	s_add_u32 s44, s44, 0x40080
	s_addc_u32 s45, s45, 0
	s_add_u32 s51, s48, 0x100
	s_addc_u32 s75, s49, 0
	s_mov_b32 s48, 0

.LBB0_896:
	s_ashr_i32 s23, s22, 31
	s_lshl_b64 s[26:27], s[22:23], 19
	s_add_u32 s26, s3, s26
	v_mov_b64_e32 v[0:1], 0
	v_mov_b64_e32 v[2:3], 0
	v_mov_b64_e32 v[4:5], 0
	v_mov_b64_e32 v[6:7], 0
	v_mov_b64_e32 v[8:9], 0
	v_mov_b64_e32 v[10:11], 0
	v_mov_b64_e32 v[12:13], 0
	v_mov_b64_e32 v[14:15], 0
	v_mov_b64_e32 v[16:17], 0
	v_mov_b64_e32 v[18:19], 0
	v_mov_b64_e32 v[20:21], 0
	v_mov_b64_e32 v[22:23], 0
	v_mov_b64_e32 v[24:25], 0
	v_mov_b64_e32 v[26:27], 0
	v_mov_b64_e32 v[28:29], 0
	v_mov_b64_e32 v[30:31], 0
	v_mov_b64_e32 v[32:33], 0
	v_mov_b64_e32 v[34:35], 0
	v_mov_b64_e32 v[36:37], 0
	v_mov_b64_e32 v[38:39], 0
	v_mov_b64_e32 v[40:41], 0
	v_mov_b64_e32 v[42:43], 0
	v_mov_b64_e32 v[44:45], 0
	v_mov_b64_e32 v[46:47], 0
	v_mov_b64_e32 v[48:49], 0
	v_mov_b64_e32 v[50:51], 0
	v_mov_b64_e32 v[52:53], 0
	v_mov_b64_e32 v[54:55], 0
	v_mov_b64_e32 v[56:57], 0
	v_mov_b64_e32 v[58:59], 0
	v_mov_b64_e32 v[60:61], 0
	v_mov_b64_e32 v[62:63], 0
	v_mov_b64_e32 v[64:65], 0
	v_mov_b64_e32 v[66:67], 0
	v_mov_b64_e32 v[68:69], 0
	v_mov_b64_e32 v[70:71], 0
	v_mov_b64_e32 v[72:73], 0
	v_mov_b64_e32 v[74:75], 0
	v_mov_b64_e32 v[76:77], 0
	v_mov_b64_e32 v[78:79], 0
	v_mov_b64_e32 v[80:81], 0
	v_mov_b64_e32 v[82:83], 0
	v_mov_b64_e32 v[84:85], 0
	v_mov_b64_e32 v[86:87], 0
	v_mov_b64_e32 v[88:89], 0
	v_mov_b64_e32 v[90:91], 0
	v_mov_b64_e32 v[92:93], 0
	v_mov_b64_e32 v[94:95], 0
	v_mov_b64_e32 v[96:97], 0
	v_mov_b64_e32 v[98:99], 0
	v_mov_b64_e32 v[100:101], 0
	v_mov_b64_e32 v[102:103], 0
	v_mov_b64_e32 v[104:105], 0
	v_mov_b64_e32 v[106:107], 0
	v_mov_b64_e32 v[108:109], 0
	v_mov_b64_e32 v[110:111], 0
	v_mov_b64_e32 v[112:113], 0
	v_mov_b64_e32 v[114:115], 0
	v_mov_b64_e32 v[116:117], 0
	v_mov_b64_e32 v[118:119], 0
	v_mov_b64_e32 v[120:121], 0
	v_mov_b64_e32 v[122:123], 0
	v_mov_b64_e32 v[124:125], 0
	v_mov_b64_e32 v[126:127], 0
	s_addc_u32 s27, s33, s27
	s_and_b64 vcc, exec, s[6:7]
	s_cbranch_vccnz .LBB0_899
	s_and_b64 s[10:11], s[10:11], exec
	s_cselect_b32 s23, s27, s35
	s_cselect_b32 s57, s26, s34
	s_add_u32 s10, s34, 0x40080
	s_addc_u32 s11, s35, 0
	s_add_u32 s34, s30, 0x100
	s_addc_u32 s35, s31, 0
	s_mov_b32 s30, 0

.LBB0_978:
	v_mov_b64_e32 v[0:1], 0
	v_mov_b64_e32 v[2:3], 0
	v_mov_b64_e32 v[4:5], 0
	v_mov_b64_e32 v[6:7], 0
	v_mov_b64_e32 v[8:9], 0
	v_mov_b64_e32 v[10:11], 0
	v_mov_b64_e32 v[12:13], 0
	v_mov_b64_e32 v[14:15], 0
	v_mov_b64_e32 v[16:17], 0
	v_mov_b64_e32 v[18:19], 0
	v_mov_b64_e32 v[20:21], 0
	v_mov_b64_e32 v[22:23], 0
	v_mov_b64_e32 v[24:25], 0
	v_mov_b64_e32 v[26:27], 0
	v_mov_b64_e32 v[28:29], 0
	v_mov_b64_e32 v[30:31], 0
	v_mov_b64_e32 v[32:33], 0
	v_mov_b64_e32 v[34:35], 0
	v_mov_b64_e32 v[36:37], 0
	v_mov_b64_e32 v[38:39], 0
	v_mov_b64_e32 v[40:41], 0
	v_mov_b64_e32 v[42:43], 0
	v_mov_b64_e32 v[44:45], 0
	v_mov_b64_e32 v[46:47], 0
	v_mov_b64_e32 v[48:49], 0
	v_mov_b64_e32 v[50:51], 0
	v_mov_b64_e32 v[52:53], 0
	v_mov_b64_e32 v[54:55], 0
	v_mov_b64_e32 v[56:57], 0
	v_mov_b64_e32 v[58:59], 0
	v_mov_b64_e32 v[60:61], 0
	v_mov_b64_e32 v[62:63], 0
	v_mov_b64_e32 v[64:65], 0
	v_mov_b64_e32 v[66:67], 0
	v_mov_b64_e32 v[68:69], 0
	v_mov_b64_e32 v[70:71], 0
	v_mov_b64_e32 v[72:73], 0
	v_mov_b64_e32 v[74:75], 0
	v_mov_b64_e32 v[76:77], 0
	v_mov_b64_e32 v[78:79], 0
	v_mov_b64_e32 v[80:81], 0
	v_mov_b64_e32 v[82:83], 0
	v_mov_b64_e32 v[84:85], 0
	v_mov_b64_e32 v[86:87], 0
	v_mov_b64_e32 v[88:89], 0
	v_mov_b64_e32 v[90:91], 0
	v_mov_b64_e32 v[92:93], 0
	v_mov_b64_e32 v[94:95], 0
	v_mov_b64_e32 v[96:97], 0
	v_mov_b64_e32 v[98:99], 0
	v_mov_b64_e32 v[100:101], 0
	v_mov_b64_e32 v[102:103], 0
	v_mov_b64_e32 v[104:105], 0
	v_mov_b64_e32 v[106:107], 0
	v_mov_b64_e32 v[108:109], 0
	v_mov_b64_e32 v[110:111], 0
	v_mov_b64_e32 v[112:113], 0
	v_mov_b64_e32 v[114:115], 0
	v_mov_b64_e32 v[116:117], 0
	v_mov_b64_e32 v[118:119], 0
	v_mov_b64_e32 v[120:121], 0
	v_mov_b64_e32 v[122:123], 0
	v_mov_b64_e32 v[124:125], 0
	v_mov_b64_e32 v[126:127], 0
	s_andn2_b64 vcc, exec, s[20:21]
	s_cbranch_vccnz .LBB0_981
	s_add_u32 s36, s36, 0xb0080
	s_addc_u32 s37, s37, 0
	s_add_u32 s67, s38, 0x100
	s_addc_u32 s68, s39, 0
	s_mov_b32 s38, 0

.LBB0_1066:
	v_mov_b64_e32 v[0:1], 0
	v_mov_b64_e32 v[2:3], 0
	v_mov_b64_e32 v[4:5], 0
	v_mov_b64_e32 v[6:7], 0
	v_mov_b64_e32 v[8:9], 0
	v_mov_b64_e32 v[10:11], 0
	v_mov_b64_e32 v[12:13], 0
	v_mov_b64_e32 v[14:15], 0
	v_mov_b64_e32 v[16:17], 0
	v_mov_b64_e32 v[18:19], 0
	v_mov_b64_e32 v[20:21], 0
	v_mov_b64_e32 v[22:23], 0
	v_mov_b64_e32 v[24:25], 0
	v_mov_b64_e32 v[26:27], 0
	v_mov_b64_e32 v[28:29], 0
	v_mov_b64_e32 v[30:31], 0
	v_mov_b64_e32 v[32:33], 0
	v_mov_b64_e32 v[34:35], 0
	v_mov_b64_e32 v[36:37], 0
	v_mov_b64_e32 v[38:39], 0
	v_mov_b64_e32 v[40:41], 0
	v_mov_b64_e32 v[42:43], 0
	v_mov_b64_e32 v[44:45], 0
	v_mov_b64_e32 v[46:47], 0
	v_mov_b64_e32 v[48:49], 0
	v_mov_b64_e32 v[50:51], 0
	v_mov_b64_e32 v[52:53], 0
	v_mov_b64_e32 v[54:55], 0
	v_mov_b64_e32 v[56:57], 0
	v_mov_b64_e32 v[58:59], 0
	v_mov_b64_e32 v[60:61], 0
	v_mov_b64_e32 v[62:63], 0
	v_mov_b64_e32 v[64:65], 0
	v_mov_b64_e32 v[66:67], 0
	v_mov_b64_e32 v[68:69], 0
	v_mov_b64_e32 v[70:71], 0
	v_mov_b64_e32 v[72:73], 0
	v_mov_b64_e32 v[74:75], 0
	v_mov_b64_e32 v[76:77], 0
	v_mov_b64_e32 v[78:79], 0
	v_mov_b64_e32 v[80:81], 0
	v_mov_b64_e32 v[82:83], 0
	v_mov_b64_e32 v[84:85], 0
	v_mov_b64_e32 v[86:87], 0
	v_mov_b64_e32 v[88:89], 0
	v_mov_b64_e32 v[90:91], 0
	v_mov_b64_e32 v[92:93], 0
	v_mov_b64_e32 v[94:95], 0
	v_mov_b64_e32 v[96:97], 0
	v_mov_b64_e32 v[98:99], 0
	v_mov_b64_e32 v[100:101], 0
	v_mov_b64_e32 v[102:103], 0
	v_mov_b64_e32 v[104:105], 0
	v_mov_b64_e32 v[106:107], 0
	v_mov_b64_e32 v[108:109], 0
	v_mov_b64_e32 v[110:111], 0
	v_mov_b64_e32 v[112:113], 0
	v_mov_b64_e32 v[114:115], 0
	v_mov_b64_e32 v[116:117], 0
	v_mov_b64_e32 v[118:119], 0
	v_mov_b64_e32 v[120:121], 0
	v_mov_b64_e32 v[122:123], 0
	v_mov_b64_e32 v[124:125], 0
	v_mov_b64_e32 v[126:127], 0
	s_andn2_b64 vcc, exec, s[16:17]
	s_cbranch_vccnz .LBB0_1069
	s_add_u32 s24, s24, 0xb0080
	s_addc_u32 s25, s25, 0
	s_add_u32 s67, s26, 0x100
	s_addc_u32 s68, s27, 0
	s_mov_b32 s26, 0

.LBB0_1234:
	s_ashr_i32 s35, s34, 31
	s_lshl_b64 s[38:39], s[34:35], 19
	s_add_u32 s38, s3, s38
	v_mov_b64_e32 v[0:1], 0
	v_mov_b64_e32 v[2:3], 0
	v_mov_b64_e32 v[4:5], 0
	v_mov_b64_e32 v[6:7], 0
	v_mov_b64_e32 v[8:9], 0
	v_mov_b64_e32 v[10:11], 0
	v_mov_b64_e32 v[12:13], 0
	v_mov_b64_e32 v[14:15], 0
	v_mov_b64_e32 v[16:17], 0
	v_mov_b64_e32 v[18:19], 0
	v_mov_b64_e32 v[20:21], 0
	v_mov_b64_e32 v[22:23], 0
	v_mov_b64_e32 v[24:25], 0
	v_mov_b64_e32 v[26:27], 0
	v_mov_b64_e32 v[28:29], 0
	v_mov_b64_e32 v[30:31], 0
	v_mov_b64_e32 v[32:33], 0
	v_mov_b64_e32 v[34:35], 0
	v_mov_b64_e32 v[36:37], 0
	v_mov_b64_e32 v[38:39], 0
	v_mov_b64_e32 v[40:41], 0
	v_mov_b64_e32 v[42:43], 0
	v_mov_b64_e32 v[44:45], 0
	v_mov_b64_e32 v[46:47], 0
	v_mov_b64_e32 v[48:49], 0
	v_mov_b64_e32 v[50:51], 0
	v_mov_b64_e32 v[52:53], 0
	v_mov_b64_e32 v[54:55], 0
	v_mov_b64_e32 v[56:57], 0
	v_mov_b64_e32 v[58:59], 0
	v_mov_b64_e32 v[60:61], 0
	v_mov_b64_e32 v[62:63], 0
	v_mov_b64_e32 v[64:65], 0
	v_mov_b64_e32 v[66:67], 0
	v_mov_b64_e32 v[68:69], 0
	v_mov_b64_e32 v[70:71], 0
	v_mov_b64_e32 v[72:73], 0
	v_mov_b64_e32 v[74:75], 0
	v_mov_b64_e32 v[76:77], 0
	v_mov_b64_e32 v[78:79], 0
	v_mov_b64_e32 v[80:81], 0
	v_mov_b64_e32 v[82:83], 0
	v_mov_b64_e32 v[84:85], 0
	v_mov_b64_e32 v[86:87], 0
	v_mov_b64_e32 v[88:89], 0
	v_mov_b64_e32 v[90:91], 0
	v_mov_b64_e32 v[92:93], 0
	v_mov_b64_e32 v[94:95], 0
	v_mov_b64_e32 v[96:97], 0
	v_mov_b64_e32 v[98:99], 0
	v_mov_b64_e32 v[100:101], 0
	v_mov_b64_e32 v[102:103], 0
	v_mov_b64_e32 v[104:105], 0
	v_mov_b64_e32 v[106:107], 0
	v_mov_b64_e32 v[108:109], 0
	v_mov_b64_e32 v[110:111], 0
	v_mov_b64_e32 v[112:113], 0
	v_mov_b64_e32 v[114:115], 0
	v_mov_b64_e32 v[116:117], 0
	v_mov_b64_e32 v[118:119], 0
	v_mov_b64_e32 v[120:121], 0
	v_mov_b64_e32 v[122:123], 0
	v_mov_b64_e32 v[124:125], 0
	v_mov_b64_e32 v[126:127], 0
	s_addc_u32 s39, s33, s39
	s_andn2_b64 vcc, exec, s[20:21]
	s_cbranch_vccnz .LBB0_1237
	s_and_b64 s[8:9], s[8:9], exec
	s_cselect_b32 s35, s39, s43
	s_cselect_b32 s67, s38, s42
	s_add_u32 s8, s42, 0x40080
	s_addc_u32 s9, s43, 0
	s_add_u32 s42, s40, 0x100
	s_addc_u32 s43, s41, 0
	s_mov_b32 s40, 0

.LBB0_1478:
	s_ashr_i32 s29, s28, 31
	s_lshl_b64 s[34:35], s[28:29], 18
	s_add_u32 s34, s33, s34
	v_mov_b64_e32 v[0:1], 0
	v_mov_b64_e32 v[2:3], 0
	v_mov_b64_e32 v[4:5], 0
	v_mov_b64_e32 v[6:7], 0
	v_mov_b64_e32 v[8:9], 0
	v_mov_b64_e32 v[10:11], 0
	v_mov_b64_e32 v[12:13], 0
	v_mov_b64_e32 v[14:15], 0
	v_mov_b64_e32 v[16:17], 0
	v_mov_b64_e32 v[18:19], 0
	v_mov_b64_e32 v[20:21], 0
	v_mov_b64_e32 v[22:23], 0
	v_mov_b64_e32 v[24:25], 0
	v_mov_b64_e32 v[26:27], 0
	v_mov_b64_e32 v[28:29], 0
	v_mov_b64_e32 v[30:31], 0
	v_mov_b64_e32 v[32:33], 0
	v_mov_b64_e32 v[34:35], 0
	v_mov_b64_e32 v[36:37], 0
	v_mov_b64_e32 v[38:39], 0
	v_mov_b64_e32 v[40:41], 0
	v_mov_b64_e32 v[42:43], 0
	v_mov_b64_e32 v[44:45], 0
	v_mov_b64_e32 v[46:47], 0
	v_mov_b64_e32 v[48:49], 0
	v_mov_b64_e32 v[50:51], 0
	v_mov_b64_e32 v[52:53], 0
	v_mov_b64_e32 v[54:55], 0
	v_mov_b64_e32 v[56:57], 0
	v_mov_b64_e32 v[58:59], 0
	v_mov_b64_e32 v[60:61], 0
	v_mov_b64_e32 v[62:63], 0
	v_mov_b64_e32 v[64:65], 0
	v_mov_b64_e32 v[66:67], 0
	v_mov_b64_e32 v[68:69], 0
	v_mov_b64_e32 v[70:71], 0
	v_mov_b64_e32 v[72:73], 0
	v_mov_b64_e32 v[74:75], 0
	v_mov_b64_e32 v[76:77], 0
	v_mov_b64_e32 v[78:79], 0
	v_mov_b64_e32 v[80:81], 0
	v_mov_b64_e32 v[82:83], 0
	v_mov_b64_e32 v[84:85], 0
	v_mov_b64_e32 v[86:87], 0
	v_mov_b64_e32 v[88:89], 0
	v_mov_b64_e32 v[90:91], 0
	v_mov_b64_e32 v[92:93], 0
	v_mov_b64_e32 v[94:95], 0
	v_mov_b64_e32 v[96:97], 0
	v_mov_b64_e32 v[98:99], 0
	v_mov_b64_e32 v[100:101], 0
	v_mov_b64_e32 v[102:103], 0
	v_mov_b64_e32 v[104:105], 0
	v_mov_b64_e32 v[106:107], 0
	v_mov_b64_e32 v[108:109], 0
	v_mov_b64_e32 v[110:111], 0
	v_mov_b64_e32 v[112:113], 0
	v_mov_b64_e32 v[114:115], 0
	v_mov_b64_e32 v[116:117], 0
	v_mov_b64_e32 v[118:119], 0
	v_mov_b64_e32 v[120:121], 0
	v_mov_b64_e32 v[122:123], 0
	v_mov_b64_e32 v[124:125], 0
	v_mov_b64_e32 v[126:127], 0
	s_addc_u32 s35, s43, s35
	s_and_b64 vcc, exec, s[6:7]
	s_cbranch_vccnz .LBB0_1481
	s_and_b64 s[10:11], s[10:11], exec
	s_cselect_b32 s29, s35, s39
	s_cselect_b32 s62, s34, s38
	s_add_u32 s10, s38, 0x20080
	s_addc_u32 s11, s39, 0
	s_add_u32 s38, s36, 0x100
	s_addc_u32 s39, s37, 0
	s_mov_b32 s36, 0

.LBB0_1499:
	s_ashr_i32 s27, s26, 31
	s_lshl_b64 s[4:5], s[26:27], 17
	s_add_u32 s30, s41, s4
	v_mov_b64_e32 v[4:5], 0
	v_mov_b64_e32 v[6:7], 0
	v_mov_b64_e32 v[8:9], 0
	v_mov_b64_e32 v[10:11], 0
	v_mov_b64_e32 v[12:13], 0
	v_mov_b64_e32 v[14:15], 0
	v_mov_b64_e32 v[16:17], 0
	v_mov_b64_e32 v[18:19], 0
	v_mov_b64_e32 v[20:21], 0
	v_mov_b64_e32 v[22:23], 0
	v_mov_b64_e32 v[24:25], 0
	v_mov_b64_e32 v[26:27], 0
	v_mov_b64_e32 v[28:29], 0
	v_mov_b64_e32 v[30:31], 0
	v_mov_b64_e32 v[32:33], 0
	v_mov_b64_e32 v[34:35], 0
	v_mov_b64_e32 v[36:37], 0
	v_mov_b64_e32 v[38:39], 0
	v_mov_b64_e32 v[40:41], 0
	v_mov_b64_e32 v[42:43], 0
	v_mov_b64_e32 v[44:45], 0
	v_mov_b64_e32 v[46:47], 0
	v_mov_b64_e32 v[48:49], 0
	v_mov_b64_e32 v[50:51], 0
	v_mov_b64_e32 v[52:53], 0
	v_mov_b64_e32 v[54:55], 0
	v_mov_b64_e32 v[56:57], 0
	v_mov_b64_e32 v[58:59], 0
	v_mov_b64_e32 v[60:61], 0
	v_mov_b64_e32 v[62:63], 0
	v_mov_b64_e32 v[64:65], 0
	v_mov_b64_e32 v[66:67], 0
	v_mov_b64_e32 v[92:93], 0
	v_mov_b64_e32 v[94:95], 0
	v_mov_b64_e32 v[96:97], 0
	v_mov_b64_e32 v[98:99], 0
	v_mov_b64_e32 v[100:101], 0
	v_mov_b64_e32 v[102:103], 0
	v_mov_b64_e32 v[104:105], 0
	v_mov_b64_e32 v[106:107], 0
	v_mov_b64_e32 v[108:109], 0
	v_mov_b64_e32 v[110:111], 0
	v_mov_b64_e32 v[112:113], 0
	v_mov_b64_e32 v[114:115], 0
	v_mov_b64_e32 v[116:117], 0
	v_mov_b64_e32 v[118:119], 0
	v_mov_b64_e32 v[120:121], 0
	v_mov_b64_e32 v[122:123], 0
	v_mov_b64_e32 v[124:125], 0
	v_mov_b64_e32 v[126:127], 0
	v_mov_b64_e32 v[128:129], 0
	v_mov_b64_e32 v[130:131], 0
	v_mov_b64_e32 v[132:133], 0
	v_mov_b64_e32 v[134:135], 0
	v_mov_b64_e32 v[136:137], 0
	v_mov_b64_e32 v[138:139], 0
	v_mov_b64_e32 v[140:141], 0
	v_mov_b64_e32 v[142:143], 0
	v_mov_b64_e32 v[144:145], 0
	v_mov_b64_e32 v[146:147], 0
	v_mov_b64_e32 v[148:149], 0
	v_mov_b64_e32 v[150:151], 0
	v_mov_b64_e32 v[152:153], 0
	v_mov_b64_e32 v[154:155], 0
	s_addc_u32 s31, s42, s5
	s_and_b64 vcc, exec, s[10:11]
	s_cbranch_vccnz .LBB0_1502
	s_and_b64 s[4:5], s[14:15], exec
	s_cselect_b32 s27, s31, s39
	s_cselect_b32 s35, s30, s38
	s_add_u32 s4, s38, 0x10080
	s_addc_u32 s5, s39, 0
	s_add_u32 s36, s36, 0x100
	s_addc_u32 s37, s37, 0
	s_mov_b32 s14, 0

.LBB0_1594:
	s_or_b64 exec, exec, s[4:5]
	v_readfirstlane_b32 s60, v109
	s_add_u32 s56, s10, s50
	s_addc_u32 s57, s11, s51
	s_lshl_b32 s60, s60, 11
	s_add_u32 s56, s56, 0x12c00000
	s_addc_u32 s57, s57, 0
	s_add_u32 s58, s10, s52
	s_addc_u32 s59, s11, s53
	s_add_u32 s58, s58, 0x1bc00000
	s_addc_u32 s59, s59, 0
	v_add_u32_e32 v134, 0xc000, v115
	s_add_i32 m0, s60, 0x0
	s_nop 0
	global_load_lds_dwordx4 v124, s[56:57]
	global_load_lds_dwordx4 v126, s[56:57] offset:1024
	s_add_u32 s56, s56, 0x4000
	s_addc_u32 s57, s57, 0
	s_add_i32 m0, s60, 0x4000
	s_nop 0
	global_load_lds_dwordx4 v124, s[56:57]
	global_load_lds_dwordx4 v126, s[56:57] offset:1024
	s_add_u32 s56, s56, 0x4000
	s_addc_u32 s57, s57, 0
	s_add_i32 m0, s60, 0xc000
	s_nop 0
	global_load_lds_dwordx4 v128, s[58:59]
	s_add_u32 s58, s58, 0x2000
	s_addc_u32 s59, s59, 0
	s_add_i32 m0, s60, 0x8000
	s_nop 0
	global_load_lds_dwordx4 v124, s[56:57]
	global_load_lds_dwordx4 v126, s[56:57] offset:1024
	s_add_u32 s56, s56, 0x4000
	s_addc_u32 s57, s57, 0
	s_add_i32 m0, s60, 0x10000
	s_nop 0
	global_load_lds_dwordx4 v128, s[58:59]
	s_add_u32 s58, s58, 0x2000
	s_addc_u32 s59, s59, 0
	v_mov_b64_e32 v[0:1], 0
	v_mov_b64_e32 v[2:3], 0
	v_mov_b64_e32 v[4:5], 0
	v_mov_b64_e32 v[6:7], 0
	v_mov_b64_e32 v[8:9], 0
	v_mov_b64_e32 v[10:11], 0
	v_mov_b64_e32 v[12:13], 0
	v_mov_b64_e32 v[14:15], 0
	v_mov_b64_e32 v[16:17], 0
	v_mov_b64_e32 v[18:19], 0
	v_mov_b64_e32 v[20:21], 0
	v_mov_b64_e32 v[22:23], 0
	v_mov_b64_e32 v[24:25], 0
	v_mov_b64_e32 v[26:27], 0
	v_mov_b64_e32 v[28:29], 0
	v_mov_b64_e32 v[30:31], 0
	v_mov_b32_e32 v133, 0
	v_mov_b32_e32 v135, 0
	s_waitcnt vmcnt(6)
	s_barrier
	ds_read_b128 v[156:159], v146 offset:0
	ds_read_b128 v[160:163], v146 offset:8192
	ds_read_b128 v[164:167], v147 offset:0
	ds_read_b128 v[168:171], v147 offset:8192
	ds_read_b128 v[172:175], v148 offset:0
	ds_read_b128 v[176:179], v148 offset:8192
	ds_read_b128 v[180:183], v149 offset:0
	ds_read_b128 v[184:187], v149 offset:8192
	ds_read_b128 v[64:67], v150 offset:0
	ds_read_b128 v[68:71], v150 offset:8192
	ds_read_b128 v[72:75], v151 offset:0
	ds_read_b128 v[76:79], v151 offset:8192
	s_waitcnt lgkmcnt(0)
	v_mfma_f32_32x32x16_bf16 v[32:47], v[156:159], v[86:89], 0
	v_mfma_f32_32x32x16_bf16 v[48:63], v[160:163], v[86:89], 0
	v_mfma_f32_32x32x16_bf16 v[32:47], v[164:167], v[82:85], v[32:47]
	v_mfma_f32_32x32x16_bf16 v[48:63], v[168:171], v[82:85], v[48:63]
	v_mfma_f32_32x32x16_bf16 v[32:47], v[172:175], v[90:93], v[32:47]
	v_mfma_f32_32x32x16_bf16 v[48:63], v[176:179], v[90:93], v[48:63]
	v_mfma_f32_32x32x16_bf16 v[32:47], v[180:183], v[94:97], v[32:47]
	v_mfma_f32_32x32x16_bf16 v[48:63], v[184:187], v[94:97], v[48:63]
	v_mfma_f32_32x32x16_bf16 v[32:47], v[64:67], v[98:101], v[32:47]
	v_mfma_f32_32x32x16_bf16 v[48:63], v[68:71], v[98:101], v[48:63]
	v_mfma_f32_32x32x16_bf16 v[32:47], v[72:75], v[102:105], v[32:47]
	v_mfma_f32_32x32x16_bf16 v[48:63], v[76:79], v[102:105], v[48:63]
	s_waitcnt vmcnt(3) lgkmcnt(0)
	s_barrier
	ds_read_b128 v[156:159], v146 offset:16384
	ds_read_b128 v[160:163], v146 offset:24576
	ds_read_b128 v[164:167], v147 offset:16384
	ds_read_b128 v[168:171], v147 offset:24576
	ds_read_b128 v[172:175], v148 offset:16384
	ds_read_b128 v[176:179], v148 offset:24576
	ds_read_b128 v[180:183], v149 offset:16384
	ds_read_b128 v[184:187], v149 offset:24576
	ds_read_b128 v[64:67], v150 offset:16384
	ds_read_b128 v[68:71], v150 offset:24576
	ds_read_b128 v[72:75], v151 offset:16384
	ds_read_b128 v[76:79], v151 offset:24576
	v_exp_f32_e32 v32, v32
	v_exp_f32_e32 v33, v33
	v_exp_f32_e32 v34, v34
	v_exp_f32_e32 v35, v35
	v_exp_f32_e32 v36, v36
	v_exp_f32_e32 v37, v37
	v_exp_f32_e32 v38, v38
	v_exp_f32_e32 v39, v39
	v_exp_f32_e32 v40, v40
	v_exp_f32_e32 v41, v41
	v_exp_f32_e32 v42, v42
	v_exp_f32_e32 v43, v43
	v_exp_f32_e32 v44, v44
	v_exp_f32_e32 v45, v45
	v_exp_f32_e32 v46, v46
	v_exp_f32_e32 v47, v47
	s_add_i32 m0, s60, 0x0
	s_nop 0
	global_load_lds_dwordx4 v124, s[56:57]
	global_load_lds_dwordx4 v126, s[56:57] offset:1024
	s_add_u32 s56, s56, 0x4000
	s_addc_u32 s57, s57, 0
	s_add_i32 m0, s60, 0x14000
	s_nop 0
	global_load_lds_dwordx4 v128, s[58:59]
	s_add_u32 s58, s58, 0x2000
	s_addc_u32 s59, s59, 0
	s_mov_b32 s33, 10

.LBB0_1677:
	s_ashr_i32 s61, s60, 31
	s_lshl_b64 s[64:65], s[60:61], 19
	s_add_u32 s64, s3, s64
	v_mov_b64_e32 v[0:1], 0
	v_mov_b64_e32 v[2:3], 0
	v_mov_b64_e32 v[4:5], 0
	v_mov_b64_e32 v[6:7], 0
	v_mov_b64_e32 v[8:9], 0
	v_mov_b64_e32 v[10:11], 0
	v_mov_b64_e32 v[12:13], 0
	v_mov_b64_e32 v[14:15], 0
	v_mov_b64_e32 v[16:17], 0
	v_mov_b64_e32 v[18:19], 0
	v_mov_b64_e32 v[20:21], 0
	v_mov_b64_e32 v[22:23], 0
	v_mov_b64_e32 v[24:25], 0
	v_mov_b64_e32 v[26:27], 0
	v_mov_b64_e32 v[28:29], 0
	v_mov_b64_e32 v[30:31], 0
	v_mov_b64_e32 v[32:33], 0
	v_mov_b64_e32 v[34:35], 0
	v_mov_b64_e32 v[36:37], 0
	v_mov_b64_e32 v[38:39], 0
	v_mov_b64_e32 v[40:41], 0
	v_mov_b64_e32 v[42:43], 0
	v_mov_b64_e32 v[44:45], 0
	v_mov_b64_e32 v[46:47], 0
	v_mov_b64_e32 v[48:49], 0
	v_mov_b64_e32 v[50:51], 0
	v_mov_b64_e32 v[52:53], 0
	v_mov_b64_e32 v[54:55], 0
	v_mov_b64_e32 v[56:57], 0
	v_mov_b64_e32 v[58:59], 0
	v_mov_b64_e32 v[60:61], 0
	v_mov_b64_e32 v[62:63], 0
	v_mov_b64_e32 v[64:65], 0
	v_mov_b64_e32 v[66:67], 0
	v_mov_b64_e32 v[68:69], 0
	v_mov_b64_e32 v[70:71], 0
	v_mov_b64_e32 v[72:73], 0
	v_mov_b64_e32 v[74:75], 0
	v_mov_b64_e32 v[76:77], 0
	v_mov_b64_e32 v[78:79], 0
	v_mov_b64_e32 v[80:81], 0
	v_mov_b64_e32 v[82:83], 0
	v_mov_b64_e32 v[84:85], 0
	v_mov_b64_e32 v[86:87], 0
	v_mov_b64_e32 v[88:89], 0
	v_mov_b64_e32 v[90:91], 0
	v_mov_b64_e32 v[92:93], 0
	v_mov_b64_e32 v[94:95], 0
	v_mov_b64_e32 v[96:97], 0
	v_mov_b64_e32 v[98:99], 0
	v_mov_b64_e32 v[100:101], 0
	v_mov_b64_e32 v[102:103], 0
	v_mov_b64_e32 v[104:105], 0
	v_mov_b64_e32 v[106:107], 0
	v_mov_b64_e32 v[108:109], 0
	v_mov_b64_e32 v[110:111], 0
	v_mov_b64_e32 v[112:113], 0
	v_mov_b64_e32 v[114:115], 0
	v_mov_b64_e32 v[116:117], 0
	v_mov_b64_e32 v[118:119], 0
	v_mov_b64_e32 v[124:125], 0
	v_mov_b64_e32 v[126:127], 0
	v_mov_b64_e32 v[132:133], 0
	v_mov_b64_e32 v[134:135], 0
	s_addc_u32 s65, s33, s65
	s_andn2_b64 vcc, exec, s[22:23]
	s_cbranch_vccnz .LBB0_1680
	s_and_b64 s[8:9], s[8:9], exec
	s_cselect_b32 s61, s65, s71
	s_cselect_b32 s89, s64, s70
	s_add_u32 s8, s70, 0x40080
	s_addc_u32 s9, s71, 0
	s_add_u32 s70, s68, 0x100
	s_addc_u32 s71, s69, 0
	s_mov_b32 s68, 0

.LBB0_1813:
	s_ashr_i32 s23, s22, 31
	s_lshl_b64 s[26:27], s[22:23], 19
	s_add_u32 s26, s3, s26
	v_mov_b64_e32 v[0:1], 0
	v_mov_b64_e32 v[2:3], 0
	v_mov_b64_e32 v[4:5], 0
	v_mov_b64_e32 v[6:7], 0
	v_mov_b64_e32 v[8:9], 0
	v_mov_b64_e32 v[10:11], 0
	v_mov_b64_e32 v[12:13], 0
	v_mov_b64_e32 v[14:15], 0
	v_mov_b64_e32 v[16:17], 0
	v_mov_b64_e32 v[18:19], 0
	v_mov_b64_e32 v[20:21], 0
	v_mov_b64_e32 v[22:23], 0
	v_mov_b64_e32 v[24:25], 0
	v_mov_b64_e32 v[26:27], 0
	v_mov_b64_e32 v[28:29], 0
	v_mov_b64_e32 v[30:31], 0
	v_mov_b64_e32 v[32:33], 0
	v_mov_b64_e32 v[34:35], 0
	v_mov_b64_e32 v[36:37], 0
	v_mov_b64_e32 v[38:39], 0
	v_mov_b64_e32 v[40:41], 0
	v_mov_b64_e32 v[42:43], 0
	v_mov_b64_e32 v[44:45], 0
	v_mov_b64_e32 v[46:47], 0
	v_mov_b64_e32 v[48:49], 0
	v_mov_b64_e32 v[50:51], 0
	v_mov_b64_e32 v[52:53], 0
	v_mov_b64_e32 v[54:55], 0
	v_mov_b64_e32 v[56:57], 0
	v_mov_b64_e32 v[58:59], 0
	v_mov_b64_e32 v[60:61], 0
	v_mov_b64_e32 v[62:63], 0
	v_mov_b64_e32 v[64:65], 0
	v_mov_b64_e32 v[66:67], 0
	v_mov_b64_e32 v[68:69], 0
	v_mov_b64_e32 v[70:71], 0
	v_mov_b64_e32 v[72:73], 0
	v_mov_b64_e32 v[74:75], 0
	v_mov_b64_e32 v[76:77], 0
	v_mov_b64_e32 v[78:79], 0
	v_mov_b64_e32 v[80:81], 0
	v_mov_b64_e32 v[82:83], 0
	v_mov_b64_e32 v[84:85], 0
	v_mov_b64_e32 v[86:87], 0
	v_mov_b64_e32 v[88:89], 0
	v_mov_b64_e32 v[90:91], 0
	v_mov_b64_e32 v[92:93], 0
	v_mov_b64_e32 v[94:95], 0
	v_mov_b64_e32 v[96:97], 0
	v_mov_b64_e32 v[98:99], 0
	v_mov_b64_e32 v[100:101], 0
	v_mov_b64_e32 v[102:103], 0
	v_mov_b64_e32 v[104:105], 0
	v_mov_b64_e32 v[106:107], 0
	v_mov_b64_e32 v[108:109], 0
	v_mov_b64_e32 v[110:111], 0
	v_mov_b64_e32 v[112:113], 0
	v_mov_b64_e32 v[114:115], 0
	v_mov_b64_e32 v[116:117], 0
	v_mov_b64_e32 v[118:119], 0
	v_mov_b64_e32 v[120:121], 0
	v_mov_b64_e32 v[122:123], 0
	v_mov_b64_e32 v[124:125], 0
	v_mov_b64_e32 v[126:127], 0
	s_addc_u32 s27, s33, s27
	s_and_b64 vcc, exec, s[6:7]
	s_cbranch_vccnz .LBB0_1816
	s_and_b64 s[10:11], s[10:11], exec
	s_cselect_b32 s23, s27, s35
	s_cselect_b32 s56, s26, s34
	s_add_u32 s10, s34, 0x40080
	s_addc_u32 s11, s35, 0
	s_add_u32 s34, s30, 0x100
	s_addc_u32 s35, s31, 0
	s_mov_b32 s30, 0

.LBB0_1895:
	v_mov_b64_e32 v[0:1], 0
	v_mov_b64_e32 v[2:3], 0
	v_mov_b64_e32 v[4:5], 0
	v_mov_b64_e32 v[6:7], 0
	v_mov_b64_e32 v[8:9], 0
	v_mov_b64_e32 v[10:11], 0
	v_mov_b64_e32 v[12:13], 0
	v_mov_b64_e32 v[14:15], 0
	v_mov_b64_e32 v[16:17], 0
	v_mov_b64_e32 v[18:19], 0
	v_mov_b64_e32 v[20:21], 0
	v_mov_b64_e32 v[22:23], 0
	v_mov_b64_e32 v[24:25], 0
	v_mov_b64_e32 v[26:27], 0
	v_mov_b64_e32 v[28:29], 0
	v_mov_b64_e32 v[30:31], 0
	v_mov_b64_e32 v[32:33], 0
	v_mov_b64_e32 v[34:35], 0
	v_mov_b64_e32 v[36:37], 0
	v_mov_b64_e32 v[38:39], 0
	v_mov_b64_e32 v[40:41], 0
	v_mov_b64_e32 v[42:43], 0
	v_mov_b64_e32 v[44:45], 0
	v_mov_b64_e32 v[46:47], 0
	v_mov_b64_e32 v[48:49], 0
	v_mov_b64_e32 v[50:51], 0
	v_mov_b64_e32 v[52:53], 0
	v_mov_b64_e32 v[54:55], 0
	v_mov_b64_e32 v[56:57], 0
	v_mov_b64_e32 v[58:59], 0
	v_mov_b64_e32 v[60:61], 0
	v_mov_b64_e32 v[62:63], 0
	v_mov_b64_e32 v[64:65], 0
	v_mov_b64_e32 v[66:67], 0
	v_mov_b64_e32 v[68:69], 0
	v_mov_b64_e32 v[70:71], 0
	v_mov_b64_e32 v[72:73], 0
	v_mov_b64_e32 v[74:75], 0
	v_mov_b64_e32 v[76:77], 0
	v_mov_b64_e32 v[78:79], 0
	v_mov_b64_e32 v[80:81], 0
	v_mov_b64_e32 v[82:83], 0
	v_mov_b64_e32 v[84:85], 0
	v_mov_b64_e32 v[86:87], 0
	v_mov_b64_e32 v[88:89], 0
	v_mov_b64_e32 v[90:91], 0
	v_mov_b64_e32 v[92:93], 0
	v_mov_b64_e32 v[94:95], 0
	v_mov_b64_e32 v[96:97], 0
	v_mov_b64_e32 v[98:99], 0
	v_mov_b64_e32 v[100:101], 0
	v_mov_b64_e32 v[102:103], 0
	v_mov_b64_e32 v[104:105], 0
	v_mov_b64_e32 v[106:107], 0
	v_mov_b64_e32 v[108:109], 0
	v_mov_b64_e32 v[110:111], 0
	v_mov_b64_e32 v[112:113], 0
	v_mov_b64_e32 v[114:115], 0
	v_mov_b64_e32 v[116:117], 0
	v_mov_b64_e32 v[118:119], 0
	v_mov_b64_e32 v[120:121], 0
	v_mov_b64_e32 v[122:123], 0
	v_mov_b64_e32 v[124:125], 0
	v_mov_b64_e32 v[126:127], 0
	s_andn2_b64 vcc, exec, s[20:21]
	s_cbranch_vccnz .LBB0_1898
	s_add_u32 s36, s36, 0xb0080
	s_addc_u32 s37, s37, 0
	s_add_u32 s61, s38, 0x100
	s_addc_u32 s62, s39, 0
	s_mov_b32 s38, 0
